# O1 stagger delay 8us (2 x s_sleep 127)
# baseline (speedup 1.0000x reference)
;   DI u16* Wt_in_o() const { return (u16*)(ws + WS_Wt_in_o); }
;   DI u16* y0b() const { return (u16*)(ws + WS_y0b); }
;   DI u16* sqb() const { return (u16*)(ws + WS_sqb); }
;   DI u16* skb() const { return (u16*)(ws + WS_skb); }
;   DI u16* svb() const { return (u16*)(ws + WS_svb); }
;   DI u16* sgb() const { return (u16*)(ws + WS_sgb); }
; DI int otid() { int t = threadIdx.x; asm volatile("" : "+v"(t)); return t; }
; DI float silu(float x) { return x * __builtin_amdgcn_rcpf(1.f + __expf(-x)); }
; DI void st_bf4(u16* d, float a, float b, float c, float e) { *(uint2*)d = pack4(a, b, c, e); }
;   const int tid = otid(), c4 = (tid & 31) * 4;
;   for (int pp = 0; pp < npass; ++pp) {
;     const int row = pp * 8 + (tid >> 5);
;     const int tok = mt * 128 + row0 + row;
;     const bool smp = tok >= TP;
;     float4 v = *(const float4*)(Cs + row * CS_LD + c4);
;     const int sec = nt >> 3; const int col = (nt & 7) * 128 + c4;
;     if (sec == 0) st_bf4(p.sqb() + (size_t)tok * 1024 + col, v.x * QS_64, v.y * QS_64, v.z * QS_64, v.w * QS_64);
;     else if (sec == 1) {
;       float* d = smp ? p.out + OFF_SK_S + (size_t)(tok - TP) * 1024 + col : p.out + OFF_SK_P + (size_t)tok * 1024 + col;
;       st_nt4(d, v); st_bf4(p.skb() + (size_t)tok * 1024 + col, v.x, v.y, v.z, v.w);
;     } else if (sec == 2) {
;       float* d = smp ? p.out + OFF_SV_S + (size_t)(tok - TP) * 1024 + col : p.out + OFF_SV_P + (size_t)tok * 1024 + col;
;       st_nt4(d, v); st_bf4(p.svb() + (size_t)tok * 1024 + col, v.x, v.y, v.z, v.w);
;     } else st_bf4(p.sgb() + (size_t)tok * 1024 + col, silu(v.x), silu(v.y), silu(v.z), silu(v.w));
;   }
; __global__ void __launch_bounds__(256, 2) fwd_megakernel(Params p) {
;     ...
;   for (TileSched ts = tile_sched(128 * 16); ts.t < ts.hi; ts.t += ts.step) {
;     const int mt = ts.t >> 4, n2 = ts.t & 15;
;     gemm_tile_wide<1024>(p.y0b(), 1024, p.Wt_in_o(), 1024, mt * 128, n2 * 256, smem, [&](int half) { epi_o1(p, mt, 2 * n2 + half, (const float*)smem); });
.LBB0_923:
	s_getreg_b32 s99, hwreg(HW_REG_LDS_ALLOC, 0, 12)
	s_cmp_eq_u32 s99, 0
	s_cbranch_scc1 .Lstag_o1
	s_sleep 127
	s_sleep 127
.Lstag_o1:
	s_add_u32 s10, s86, 0xddf0000
	s_addc_u32 s11, s87, 0
	s_add_u32 s12, s86, 0x29c8000
	s_addc_u32 s13, s87, 0
	s_add_u32 s14, s84, 0xcc00000
	s_addc_u32 s15, s85, 0
	s_add_u32 s16, s84, 0x11050000
	s_addc_u32 s17, s85, 0
	s_add_u32 s20, s86, 0x140f0000
	s_addc_u32 s21, s87, 0
	s_add_u32 s22, s84, 0x8c00000
	s_addc_u32 s23, s85, 0
	s_add_u32 s24, s84, 0x10e50000
	s_addc_u32 s25, s85, 0
	s_add_u32 s26, s86, 0x11ff0000
	s_addc_u32 s27, s87, 0
	s_add_u32 s28, s86, 0x161f0000
	s_addc_u32 s29, s87, 0
	s_add_u32 s30, s86, 0xfef0000
	s_addc_u32 s31, s87, 0
	s_add_u32 s36, s86, 0xddf0040
	s_addc_u32 s37, s87, 0
	s_lshl_b32 s47, s34, 3
	s_lshl_b32 s48, s33, 3
	s_add_u32 s40, s86, 0x29c8040
	s_addc_u32 s41, s87, 0
	v_mov_b32_e32 v133, 0
	s_mov_b64 s[42:43], 0x40000
	s_mov_b64 s[44:45], 0x60000
	s_movk_i32 s49, 0x4000
	s_movk_i32 s52, 0x210
	s_mov_b32 s46, 0x3e38aa3b
	s_mov_b32 s53, s34
	s_waitcnt vmcnt(0)
	s_branch .LBB0_926
